# v44 with phase C main loop head moved from 48 to 0 mod 64 (compensated after loop)
# speedup vs baseline: 1.0053x; 1.0010x over previous
.LBB0_184:
	s_ashr_i32 s11, s10, 31
	s_lshl_b64 s[14:15], s[10:11], 20
	v_readlane_b32 s16, v252, 6
	v_readlane_b32 s17, v252, 7
	s_add_u32 s14, s16, s14
	s_addc_u32 s15, s17, s15
	s_and_b64 s[16:17], s[0:1], exec
	s_cselect_b32 s11, s15, s19
	s_cselect_b32 s37, s14, s18
	s_ashr_i32 s13, s12, 31
	s_lshl_b64 s[16:17], s[12:13], 20
	s_add_u32 s16, s52, s16
	s_addc_u32 s17, s53, s17
	s_and_b64 s[22:23], s[0:1], exec
	s_cselect_b32 s13, s17, s21
	s_cselect_b32 s38, s16, s20
	s_add_u32 s18, s18, 0x80080
	s_addc_u32 s19, s19, 0
	s_add_u32 s39, s20, 0x100
	v_mov_b32_e32 v0, 0
	s_addc_u32 s40, s21, 0
	s_mov_b32 s41, -2
	v_mov_b32_e32 v1, v0
	v_mov_b32_e32 v2, v0
	v_mov_b32_e32 v3, v0
	v_mov_b32_e32 v4, v0
	v_mov_b32_e32 v5, v0
	v_mov_b32_e32 v6, v0
	v_mov_b32_e32 v7, v0
	v_mov_b32_e32 v8, v0
	v_mov_b32_e32 v9, v0
	v_mov_b32_e32 v10, v0
	v_mov_b32_e32 v11, v0
	v_mov_b32_e32 v12, v0
	v_mov_b32_e32 v13, v0
	v_mov_b32_e32 v14, v0
	v_mov_b32_e32 v15, v0
	v_mov_b32_e32 v24, v0
	v_mov_b32_e32 v25, v0
	v_mov_b32_e32 v26, v0
	v_mov_b32_e32 v27, v0
	v_mov_b32_e32 v28, v0
	v_mov_b32_e32 v29, v0
	v_mov_b32_e32 v30, v0
	v_mov_b32_e32 v31, v0
	v_mov_b32_e32 v40, v0
	v_mov_b32_e32 v41, v0
	v_mov_b32_e32 v42, v0
	v_mov_b32_e32 v43, v0
	v_mov_b32_e32 v44, v0
	v_mov_b32_e32 v45, v0
	v_mov_b32_e32 v46, v0
	v_mov_b32_e32 v47, v0
	v_mov_b32_e32 v16, v0
	v_mov_b32_e32 v17, v0
	v_mov_b32_e32 v18, v0
	v_mov_b32_e32 v19, v0
	v_mov_b32_e32 v20, v0
	v_mov_b32_e32 v21, v0
	v_mov_b32_e32 v22, v0
	v_mov_b32_e32 v23, v0
	v_mov_b32_e32 v32, v0
	v_mov_b32_e32 v33, v0
	v_mov_b32_e32 v34, v0
	v_mov_b32_e32 v35, v0
	v_mov_b32_e32 v36, v0
	v_mov_b32_e32 v37, v0
	v_mov_b32_e32 v38, v0
	v_mov_b32_e32 v39, v0
	v_mov_b32_e32 v48, v0
	v_mov_b32_e32 v49, v0
	v_mov_b32_e32 v50, v0
	v_mov_b32_e32 v51, v0
	v_mov_b32_e32 v52, v0
	v_mov_b32_e32 v53, v0
	v_mov_b32_e32 v54, v0
	v_mov_b32_e32 v55, v0
	v_mov_b32_e32 v56, v0
	v_mov_b32_e32 v57, v0
	v_mov_b32_e32 v58, v0
	v_mov_b32_e32 v59, v0
	v_mov_b32_e32 v60, v0
	v_mov_b32_e32 v61, v0
	v_mov_b32_e32 v62, v0
	v_mov_b32_e32 v63, v0
	v_mov_b32_e32 v64, v0
	v_mov_b32_e32 v65, v0
	v_mov_b32_e32 v66, v0
	v_mov_b32_e32 v67, v0
	v_mov_b32_e32 v68, v0
	v_mov_b32_e32 v69, v0
	v_mov_b32_e32 v70, v0
	v_mov_b32_e32 v71, v0
	v_mov_b32_e32 v72, v0
	v_mov_b32_e32 v73, v0
	v_mov_b32_e32 v74, v0
	v_mov_b32_e32 v75, v0
	v_mov_b32_e32 v76, v0
	v_mov_b32_e32 v77, v0
	v_mov_b32_e32 v78, v0
	v_mov_b32_e32 v79, v0
	v_mov_b32_e32 v88, v0
	v_mov_b32_e32 v89, v0
	v_mov_b32_e32 v90, v0
	v_mov_b32_e32 v91, v0
	v_mov_b32_e32 v92, v0
	v_mov_b32_e32 v93, v0
	v_mov_b32_e32 v94, v0
	v_mov_b32_e32 v95, v0
	v_mov_b32_e32 v104, v0
	v_mov_b32_e32 v105, v0
	v_mov_b32_e32 v106, v0
	v_mov_b32_e32 v107, v0
	v_mov_b32_e32 v108, v0
	v_mov_b32_e32 v109, v0
	v_mov_b32_e32 v110, v0
	v_mov_b32_e32 v111, v0
	v_mov_b32_e32 v80, v0
	v_mov_b32_e32 v81, v0
	v_mov_b32_e32 v82, v0
	v_mov_b32_e32 v83, v0
	v_mov_b32_e32 v84, v0
	v_mov_b32_e32 v85, v0
	v_mov_b32_e32 v86, v0
	v_mov_b32_e32 v87, v0
	v_mov_b32_e32 v96, v0
	v_mov_b32_e32 v97, v0
	v_mov_b32_e32 v98, v0
	v_mov_b32_e32 v99, v0
	v_mov_b32_e32 v100, v0
	v_mov_b32_e32 v101, v0
	v_mov_b32_e32 v102, v0
	v_mov_b32_e32 v103, v0
	v_mov_b32_e32 v112, v0
	v_mov_b32_e32 v113, v0
	v_mov_b32_e32 v114, v0
	v_mov_b32_e32 v115, v0
	v_mov_b32_e32 v116, v0
	v_mov_b32_e32 v117, v0
	v_mov_b32_e32 v118, v0
	v_mov_b32_e32 v119, v0
	v_mov_b32_e32 v120, v0
	v_mov_b32_e32 v121, v0
	v_mov_b32_e32 v122, v0
	v_mov_b32_e32 v123, v0
	v_mov_b32_e32 v124, v0
	v_mov_b32_e32 v125, v0
	v_mov_b32_e32 v126, v0
	v_mov_b32_e32 v127, v0
	s_nop 0
	s_nop 0
	s_nop 0
	s_nop 0
.LBB0_185:
	ds_read_b128 v[148:151], v144
	ds_read_b128 v[152:155], v144 offset:1024
	ds_read_b128 v[156:159], v144 offset:2048
	ds_read_b128 v[160:163], v144 offset:3072
	ds_read_b128 v[164:167], v145
	ds_read_b128 v[168:171], v145 offset:1024
	ds_read_b128 v[172:175], v145 offset:2048
	ds_read_b128 v[176:179], v145 offset:3072
	s_add_u32 s20, s18, 0xfff80080
	s_addc_u32 s21, s19, -1
	s_cmp_eq_u32 s41, 28
	s_cselect_b32 s23, s11, s21
	s_cselect_b32 s22, s37, s20
	s_cselect_b32 s21, s13, s40
	s_cselect_b32 s20, s38, s39
	v_lshl_add_u64 v[180:181], s[18:19], 0, v[134:135]
	s_add_i32 m0, s3, 0xc000
	ds_read_b128 v[184:187], v146
	ds_read_b128 v[188:191], v146 offset:1024
	ds_read_b128 v[192:195], v146 offset:2048
	ds_read_b128 v[196:199], v146 offset:3072
	ds_read_b128 v[200:203], v146 offset:4096
	ds_read_b128 v[204:207], v146 offset:5120
	ds_read_b128 v[208:211], v146 offset:6144
	ds_read_b128 v[212:215], v146 offset:7168
	global_load_lds_dwordx4 v[180:181], off
	v_lshl_add_u64 v[180:181], s[18:19], 0, v[136:137]
	s_add_i32 m0, s3, 0xe000
	s_nop 0
	global_load_lds_dwordx4 v[180:181], off
	s_waitcnt vmcnt(8)
	s_waitcnt lgkmcnt(0)
	s_barrier
	s_setprio 1
	s_waitcnt lgkmcnt(0)
	v_mfma_f32_16x16x32_bf16 v[124:127], v[148:151], v[184:187], v[124:127]
	v_mfma_f32_16x16x32_bf16 v[120:123], v[156:159], v[184:187], v[120:123]
	v_mfma_f32_16x16x32_bf16 v[116:119], v[148:151], v[192:195], v[116:119]
	v_mfma_f32_16x16x32_bf16 v[112:115], v[156:159], v[192:195], v[112:115]
	v_mfma_f32_16x16x32_bf16 v[100:103], v[148:151], v[200:203], v[100:103]
	v_mfma_f32_16x16x32_bf16 v[96:99], v[156:159], v[200:203], v[96:99]
	v_mfma_f32_16x16x32_bf16 v[84:87], v[148:151], v[208:211], v[84:87]
	v_mfma_f32_16x16x32_bf16 v[80:83], v[156:159], v[208:211], v[80:83]
	v_mfma_f32_16x16x32_bf16 v[124:127], v[152:155], v[188:191], v[124:127]
	v_mfma_f32_16x16x32_bf16 v[120:123], v[160:163], v[188:191], v[120:123]
	v_mfma_f32_16x16x32_bf16 v[116:119], v[152:155], v[196:199], v[116:119]
	v_mfma_f32_16x16x32_bf16 v[112:115], v[160:163], v[196:199], v[112:115]
	v_mfma_f32_16x16x32_bf16 v[100:103], v[152:155], v[204:207], v[100:103]
	v_mfma_f32_16x16x32_bf16 v[96:99], v[160:163], v[204:207], v[96:99]
	v_mfma_f32_16x16x32_bf16 v[84:87], v[152:155], v[212:215], v[84:87]
	v_mfma_f32_16x16x32_bf16 v[80:83], v[160:163], v[212:215], v[80:83]
	s_setprio 0
	s_setprio 1
	v_mfma_f32_16x16x32_bf16 v[108:111], v[164:167], v[184:187], v[108:111]
	v_mfma_f32_16x16x32_bf16 v[104:107], v[172:175], v[184:187], v[104:107]
	v_mfma_f32_16x16x32_bf16 v[92:95], v[164:167], v[192:195], v[92:95]
	v_mfma_f32_16x16x32_bf16 v[88:91], v[172:175], v[192:195], v[88:91]
	v_mfma_f32_16x16x32_bf16 v[76:79], v[164:167], v[200:203], v[76:79]
	v_mfma_f32_16x16x32_bf16 v[72:75], v[172:175], v[200:203], v[72:75]
	v_mfma_f32_16x16x32_bf16 v[68:71], v[164:167], v[208:211], v[68:71]
	v_mfma_f32_16x16x32_bf16 v[64:67], v[172:175], v[208:211], v[64:67]
	v_mfma_f32_16x16x32_bf16 v[108:111], v[168:171], v[188:191], v[108:111]
	v_mfma_f32_16x16x32_bf16 v[104:107], v[176:179], v[188:191], v[104:107]
	v_mfma_f32_16x16x32_bf16 v[92:95], v[168:171], v[196:199], v[92:95]
	v_mfma_f32_16x16x32_bf16 v[88:91], v[176:179], v[196:199], v[88:91]
	v_mfma_f32_16x16x32_bf16 v[76:79], v[168:171], v[204:207], v[76:79]
	v_mfma_f32_16x16x32_bf16 v[72:75], v[176:179], v[204:207], v[72:75]
	v_mfma_f32_16x16x32_bf16 v[68:71], v[168:171], v[212:215], v[68:71]
	v_mfma_f32_16x16x32_bf16 v[64:67], v[176:179], v[212:215], v[64:67]
	s_setprio 0
	s_barrier
	s_add_i32 s42, s30, s2
	v_lshl_add_u64 v[180:181], s[20:21], 0, v[128:129]
	s_mov_b32 m0, s42
	ds_read_b128 v[184:187], v146 offset:16384
	ds_read_b128 v[188:191], v146 offset:17408
	ds_read_b128 v[192:195], v146 offset:18432
	ds_read_b128 v[196:199], v146 offset:19456
	ds_read_b128 v[200:203], v146 offset:20480
	ds_read_b128 v[204:207], v146 offset:21504
	ds_read_b128 v[208:211], v146 offset:22528
	ds_read_b128 v[212:215], v146 offset:23552
	global_load_lds_dwordx4 v[180:181], off
	s_add_i32 m0, s42, 0x2000
	s_add_u32 s42, s20, 0x80000
	v_lshl_add_u64 v[216:217], s[20:21], 0, v[130:131]
	s_addc_u32 s43, s21, 0
	s_add_i32 s48, s31, s2
	global_load_lds_dwordx4 v[216:217], off
	v_lshl_add_u64 v[218:219], s[42:43], 0, v[128:129]
	s_mov_b32 m0, s48
	v_lshl_add_u64 v[220:221], s[22:23], 0, v[130:131]
	global_load_lds_dwordx4 v[218:219], off
	v_lshl_add_u64 v[218:219], s[42:43], 0, v[130:131]
	s_add_i32 m0, s48, 0x2000
	s_nop 0
	global_load_lds_dwordx4 v[218:219], off
	v_lshl_add_u64 v[218:219], s[22:23], 0, v[128:129]
	s_mov_b32 m0, s3
	s_nop 0
	global_load_lds_dwordx4 v[218:219], off
	s_mov_b32 m0, s24
	s_nop 0
	global_load_lds_dwordx4 v[220:221], off
	s_waitcnt vmcnt(8)
	s_waitcnt lgkmcnt(0)
	s_barrier
	s_setprio 1
	s_waitcnt lgkmcnt(0)
	v_mfma_f32_16x16x32_bf16 v[60:63], v[148:151], v[184:187], v[60:63]
	v_mfma_f32_16x16x32_bf16 v[56:59], v[156:159], v[184:187], v[56:59]
	v_mfma_f32_16x16x32_bf16 v[52:55], v[148:151], v[192:195], v[52:55]
	v_mfma_f32_16x16x32_bf16 v[48:51], v[156:159], v[192:195], v[48:51]
	v_mfma_f32_16x16x32_bf16 v[36:39], v[148:151], v[200:203], v[36:39]
	v_mfma_f32_16x16x32_bf16 v[32:35], v[156:159], v[200:203], v[32:35]
	v_mfma_f32_16x16x32_bf16 v[20:23], v[148:151], v[208:211], v[20:23]
	v_mfma_f32_16x16x32_bf16 v[16:19], v[156:159], v[208:211], v[16:19]
	v_mfma_f32_16x16x32_bf16 v[60:63], v[152:155], v[188:191], v[60:63]
	v_mfma_f32_16x16x32_bf16 v[56:59], v[160:163], v[188:191], v[56:59]
	v_mfma_f32_16x16x32_bf16 v[52:55], v[152:155], v[196:199], v[52:55]
	v_mfma_f32_16x16x32_bf16 v[48:51], v[160:163], v[196:199], v[48:51]
	v_mfma_f32_16x16x32_bf16 v[36:39], v[152:155], v[204:207], v[36:39]
	v_mfma_f32_16x16x32_bf16 v[32:35], v[160:163], v[204:207], v[32:35]
	v_mfma_f32_16x16x32_bf16 v[20:23], v[152:155], v[212:215], v[20:23]
	v_mfma_f32_16x16x32_bf16 v[16:19], v[160:163], v[212:215], v[16:19]
	s_setprio 0
	s_setprio 1
	v_mfma_f32_16x16x32_bf16 v[44:47], v[164:167], v[184:187], v[44:47]
	v_mfma_f32_16x16x32_bf16 v[40:43], v[172:175], v[184:187], v[40:43]
	v_mfma_f32_16x16x32_bf16 v[28:31], v[164:167], v[192:195], v[28:31]
	v_mfma_f32_16x16x32_bf16 v[24:27], v[172:175], v[192:195], v[24:27]
	v_mfma_f32_16x16x32_bf16 v[12:15], v[164:167], v[200:203], v[12:15]
	v_mfma_f32_16x16x32_bf16 v[8:11], v[172:175], v[200:203], v[8:11]
	v_mfma_f32_16x16x32_bf16 v[4:7], v[164:167], v[208:211], v[4:7]
	v_mfma_f32_16x16x32_bf16 v[0:3], v[172:175], v[208:211], v[0:3]
	v_mfma_f32_16x16x32_bf16 v[44:47], v[168:171], v[188:191], v[44:47]
	v_mfma_f32_16x16x32_bf16 v[40:43], v[176:179], v[188:191], v[40:43]
	v_mfma_f32_16x16x32_bf16 v[28:31], v[168:171], v[196:199], v[28:31]
	v_mfma_f32_16x16x32_bf16 v[24:27], v[176:179], v[196:199], v[24:27]
	v_mfma_f32_16x16x32_bf16 v[12:15], v[168:171], v[204:207], v[12:15]
	v_mfma_f32_16x16x32_bf16 v[8:11], v[176:179], v[204:207], v[8:11]
	v_mfma_f32_16x16x32_bf16 v[4:7], v[168:171], v[212:215], v[4:7]
	v_mfma_f32_16x16x32_bf16 v[0:3], v[176:179], v[212:215], v[0:3]
	s_setprio 0
	s_barrier
	s_add_i32 s42, 0, 0x18000
	v_add_u32_e32 v147, s42, v143
	s_add_i32 s43, 0, 0x1c000
	ds_read_b128 v[148:151], v147
	ds_read_b128 v[152:155], v147 offset:1024
	ds_read_b128 v[156:159], v147 offset:2048
	ds_read_b128 v[160:163], v147 offset:3072
	v_add_u32_e32 v147, s43, v143
	ds_read_b128 v[164:167], v147
	ds_read_b128 v[168:171], v147 offset:1024
	ds_read_b128 v[172:175], v147 offset:2048
	ds_read_b128 v[176:179], v147 offset:3072
	s_add_u32 s22, s22, 0x80000
	s_addc_u32 s23, s23, 0
	s_mov_b32 m0, s25
	v_lshl_add_u64 v[222:223], s[22:23], 0, v[128:129]
	ds_read_b128 v[184:187], v146 offset:32768
	ds_read_b128 v[188:191], v146 offset:33792
	ds_read_b128 v[192:195], v146 offset:34816
	ds_read_b128 v[196:199], v146 offset:35840
	ds_read_b128 v[200:203], v146 offset:36864
	ds_read_b128 v[204:207], v146 offset:37888
	ds_read_b128 v[208:211], v146 offset:38912
	ds_read_b128 v[212:215], v146 offset:39936
	global_load_lds_dwordx4 v[222:223], off
	v_lshl_add_u64 v[222:223], s[22:23], 0, v[130:131]
	s_mov_b32 m0, s26
	s_nop 0
	global_load_lds_dwordx4 v[222:223], off
	s_waitcnt vmcnt(8)
	s_waitcnt lgkmcnt(0)
	s_barrier
	s_setprio 1
	s_waitcnt lgkmcnt(0)
	v_mfma_f32_16x16x32_bf16 v[124:127], v[148:151], v[184:187], v[124:127]
	v_mfma_f32_16x16x32_bf16 v[120:123], v[156:159], v[184:187], v[120:123]
	v_mfma_f32_16x16x32_bf16 v[116:119], v[148:151], v[192:195], v[116:119]
	v_mfma_f32_16x16x32_bf16 v[112:115], v[156:159], v[192:195], v[112:115]
	v_mfma_f32_16x16x32_bf16 v[100:103], v[148:151], v[200:203], v[100:103]
	v_mfma_f32_16x16x32_bf16 v[96:99], v[156:159], v[200:203], v[96:99]
	v_mfma_f32_16x16x32_bf16 v[84:87], v[148:151], v[208:211], v[84:87]
	v_mfma_f32_16x16x32_bf16 v[80:83], v[156:159], v[208:211], v[80:83]
	v_mfma_f32_16x16x32_bf16 v[124:127], v[152:155], v[188:191], v[124:127]
	v_mfma_f32_16x16x32_bf16 v[120:123], v[160:163], v[188:191], v[120:123]
	v_mfma_f32_16x16x32_bf16 v[116:119], v[152:155], v[196:199], v[116:119]
	v_mfma_f32_16x16x32_bf16 v[112:115], v[160:163], v[196:199], v[112:115]
	v_mfma_f32_16x16x32_bf16 v[100:103], v[152:155], v[204:207], v[100:103]
	v_mfma_f32_16x16x32_bf16 v[96:99], v[160:163], v[204:207], v[96:99]
	v_mfma_f32_16x16x32_bf16 v[84:87], v[152:155], v[212:215], v[84:87]
	v_mfma_f32_16x16x32_bf16 v[80:83], v[160:163], v[212:215], v[80:83]
	s_setprio 0
	s_setprio 1
	v_mfma_f32_16x16x32_bf16 v[108:111], v[164:167], v[184:187], v[108:111]
	v_mfma_f32_16x16x32_bf16 v[104:107], v[172:175], v[184:187], v[104:107]
	v_mfma_f32_16x16x32_bf16 v[92:95], v[164:167], v[192:195], v[92:95]
	v_mfma_f32_16x16x32_bf16 v[88:91], v[172:175], v[192:195], v[88:91]
	v_mfma_f32_16x16x32_bf16 v[76:79], v[164:167], v[200:203], v[76:79]
	v_mfma_f32_16x16x32_bf16 v[72:75], v[172:175], v[200:203], v[72:75]
	v_mfma_f32_16x16x32_bf16 v[68:71], v[164:167], v[208:211], v[68:71]
	v_mfma_f32_16x16x32_bf16 v[64:67], v[172:175], v[208:211], v[64:67]
	v_mfma_f32_16x16x32_bf16 v[108:111], v[168:171], v[188:191], v[108:111]
	v_mfma_f32_16x16x32_bf16 v[104:107], v[176:179], v[188:191], v[104:107]
	v_mfma_f32_16x16x32_bf16 v[92:95], v[168:171], v[196:199], v[92:95]
	v_mfma_f32_16x16x32_bf16 v[88:91], v[176:179], v[196:199], v[88:91]
	v_mfma_f32_16x16x32_bf16 v[76:79], v[168:171], v[204:207], v[76:79]
	v_mfma_f32_16x16x32_bf16 v[72:75], v[176:179], v[204:207], v[72:75]
	v_mfma_f32_16x16x32_bf16 v[68:71], v[168:171], v[212:215], v[68:71]
	v_mfma_f32_16x16x32_bf16 v[64:67], v[176:179], v[212:215], v[64:67]
	s_setprio 0
	s_barrier
	s_add_i32 s22, s42, s2
	v_lshl_add_u64 v[180:181], v[180:181], 0, s[6:7]
	s_mov_b32 m0, s22
	ds_read_b128 v[184:187], v146 offset:49152
	ds_read_b128 v[188:191], v146 offset:50176
	ds_read_b128 v[192:195], v146 offset:51200
	ds_read_b128 v[196:199], v146 offset:52224
	ds_read_b128 v[200:203], v146 offset:53248
	ds_read_b128 v[204:207], v146 offset:54272
	ds_read_b128 v[208:211], v146 offset:55296
	ds_read_b128 v[212:215], v146 offset:56320
	global_load_lds_dwordx4 v[180:181], off
	s_add_i32 m0, s22, 0x2000
	s_add_u32 s20, s20, 0x80080
	v_lshl_add_u64 v[180:181], v[216:217], 0, s[6:7]
	s_addc_u32 s21, s21, 0
	s_add_i32 s22, s43, s2
	global_load_lds_dwordx4 v[180:181], off
	v_lshl_add_u64 v[180:181], s[20:21], 0, v[128:129]
	s_mov_b32 m0, s22
	s_nop 0
	global_load_lds_dwordx4 v[180:181], off
	v_lshl_add_u64 v[180:181], s[20:21], 0, v[130:131]
	s_add_i32 m0, s22, 0x2000
	s_nop 0
	global_load_lds_dwordx4 v[180:181], off
	v_lshl_add_u64 v[180:181], v[218:219], 0, s[6:7]
	s_mov_b32 m0, s27
	s_nop 0
	global_load_lds_dwordx4 v[180:181], off
	v_lshl_add_u64 v[180:181], v[220:221], 0, s[6:7]
	s_mov_b32 m0, s28
	s_nop 0
	global_load_lds_dwordx4 v[180:181], off
	s_waitcnt vmcnt(8)
	s_waitcnt lgkmcnt(0)
	s_barrier
	s_setprio 1
	s_waitcnt lgkmcnt(0)
	v_mfma_f32_16x16x32_bf16 v[60:63], v[148:151], v[184:187], v[60:63]
	v_mfma_f32_16x16x32_bf16 v[56:59], v[156:159], v[184:187], v[56:59]
	v_mfma_f32_16x16x32_bf16 v[52:55], v[148:151], v[192:195], v[52:55]
	v_mfma_f32_16x16x32_bf16 v[48:51], v[156:159], v[192:195], v[48:51]
	v_mfma_f32_16x16x32_bf16 v[36:39], v[148:151], v[200:203], v[36:39]
	v_mfma_f32_16x16x32_bf16 v[32:35], v[156:159], v[200:203], v[32:35]
	v_mfma_f32_16x16x32_bf16 v[20:23], v[148:151], v[208:211], v[20:23]
	v_mfma_f32_16x16x32_bf16 v[16:19], v[156:159], v[208:211], v[16:19]
	v_mfma_f32_16x16x32_bf16 v[60:63], v[152:155], v[188:191], v[60:63]
	v_mfma_f32_16x16x32_bf16 v[56:59], v[160:163], v[188:191], v[56:59]
	v_mfma_f32_16x16x32_bf16 v[52:55], v[152:155], v[196:199], v[52:55]
	v_mfma_f32_16x16x32_bf16 v[48:51], v[160:163], v[196:199], v[48:51]
	v_mfma_f32_16x16x32_bf16 v[36:39], v[152:155], v[204:207], v[36:39]
	v_mfma_f32_16x16x32_bf16 v[32:35], v[160:163], v[204:207], v[32:35]
	v_mfma_f32_16x16x32_bf16 v[20:23], v[152:155], v[212:215], v[20:23]
	v_mfma_f32_16x16x32_bf16 v[16:19], v[160:163], v[212:215], v[16:19]
	s_setprio 0
	s_setprio 1
	v_mfma_f32_16x16x32_bf16 v[44:47], v[164:167], v[184:187], v[44:47]
	v_mfma_f32_16x16x32_bf16 v[40:43], v[172:175], v[184:187], v[40:43]
	v_mfma_f32_16x16x32_bf16 v[28:31], v[164:167], v[192:195], v[28:31]
	v_mfma_f32_16x16x32_bf16 v[24:27], v[172:175], v[192:195], v[24:27]
	v_mfma_f32_16x16x32_bf16 v[12:15], v[164:167], v[200:203], v[12:15]
	v_mfma_f32_16x16x32_bf16 v[8:11], v[172:175], v[200:203], v[8:11]
	v_mfma_f32_16x16x32_bf16 v[4:7], v[164:167], v[208:211], v[4:7]
	v_mfma_f32_16x16x32_bf16 v[0:3], v[172:175], v[208:211], v[0:3]
	v_mfma_f32_16x16x32_bf16 v[44:47], v[168:171], v[188:191], v[44:47]
	v_mfma_f32_16x16x32_bf16 v[40:43], v[176:179], v[188:191], v[40:43]
	v_mfma_f32_16x16x32_bf16 v[28:31], v[168:171], v[196:199], v[28:31]
	v_mfma_f32_16x16x32_bf16 v[24:27], v[176:179], v[196:199], v[24:27]
	v_mfma_f32_16x16x32_bf16 v[12:15], v[168:171], v[204:207], v[12:15]
	v_mfma_f32_16x16x32_bf16 v[8:11], v[176:179], v[204:207], v[8:11]
	v_mfma_f32_16x16x32_bf16 v[4:7], v[168:171], v[212:215], v[4:7]
	v_mfma_f32_16x16x32_bf16 v[0:3], v[176:179], v[212:215], v[0:3]
	s_setprio 0
	s_barrier
	s_add_i32 s41, s41, 2
	s_add_u32 s18, s18, 0x100
	s_addc_u32 s19, s19, 0
	s_add_u32 s39, s39, 0x100
	s_addc_u32 s40, s40, 0
	s_cmp_gt_u32 s41, 29
	s_cbranch_scc0 .LBB0_185
	s_nop 0
	s_nop 0
	s_nop 0
	s_nop 0
	s_nop 0
	s_nop 0
	s_nop 0
	s_nop 0
	s_nop 0
	s_nop 0
	s_nop 0
	s_nop 0
	s_and_b64 vcc, exec, s[8:9]
	s_cbranch_vccz .LBB0_188
	s_barrier
